# phase A K loop: next step's LDS read addresses computed before the end-of-step wait, so the first-half reads issue right after the block barrier
# speedup vs baseline: 1.0034x; 1.0034x over previous
; #define MFMA16(a, b, c) __builtin_amdgcn_mfma_f32_16x16x32_bf16((a), (b), (c), 0, 0, 0)
; DI void gemm_tile(const bf16_t* __restrict__ A, int lda, const bf16_t* __restrict__ Bt, int ldb, int bvalid, int K, f32x4 (&acc)[4][4], char* lds, bool preloaded = false) {
;     ...
;   const bf16_t* ap = A + (size_t)lr * lda + ((lc ^ ((lr >> 1) & 7)) << 3);
;   const bf16_t* bp = Bt + ((lc ^ ((lr >> 1) & 7)) << 3);
;   typedef __attribute__((address_space(1))) const unsigned gptr_t;
;   typedef __attribute__((address_space(3))) unsigned lptr_t;
;   const unsigned lbase = (unsigned)(size_t)lds + (unsigned)tid * 16u;
;     ...
;   auto compute = [&](int st) {
;     const char* base = lds + st * 32768;
;     bf16x8 af[2][4], bfr[2][4];
; #pragma unroll
;     for (int s = 0; s < 2; ++s) {
;       const int ch = ((4 * s + fq) ^ fx) << 4;
; #pragma unroll
;       for (int mi = 0; mi < 4; ++mi) af[s][mi] = *(const bf16x8*)(base + (wm * 64 + mi * 16 + fr) * 128 + ch);
; #pragma unroll
;       for (int ni = 0; ni < 4; ++ni) bfr[s][ni] = *(const bf16x8*)(base + 16384 + (wn * 64 + ni * 16 + fr) * 128 + ch);
;     }
;     __builtin_amdgcn_s_setprio(1);
; #pragma unroll
;     for (int s = 0; s < 2; ++s)
; #pragma unroll
;       for (int mi = 0; mi < 4; ++mi)
; #pragma unroll
;         for (int ni = 0; ni < 4; ++ni) acc[mi][ni] = MFMA16(af[s][mi], bfr[s][ni], acc[mi][ni]);
;     __builtin_amdgcn_s_setprio(0);
;   };
;   const int nk = K >> 6;
;   if (!preloaded) { GLDS(0, 0) }
;   __syncthreads();
; DI void phaseA_tile(const P& p, int layer, int mt, int nt, char* lds) {
;     ...
;   const float* sp = (const float*)(p.ws + W_SS) + (size_t)(row0 + (tid & 127)) * 16;
;   const f32x4 ssa = *(const f32x4*)sp, ssb = *(const f32x4*)(sp + 4), ssc = *(const f32x4*)(sp + 8), ssd = *(const f32x4*)(sp + 12);
;   f32x4 acc[4][4];
;   zero_acc(acc);
;   gemm_tile((const bf16_t*)(p.ws + W_XB) + (size_t)row0 * DM, DM, (const bf16_t*)(p.ws + W_WIN) + ((size_t)layer * NP + col0) * 1024, 1024, bvalid, 1024, acc, lds);
;   const int wm = wave >> 1, wn = wave & 1;
;   const int seg = (col0 >> 6) + wn;
;   const int fr = lane & 15, fq = lane >> 4;
;   if (tid < 128) {
;     const float ss = (ssa.x + ssa.y + ssa.z + ssa.w) + (ssb.x + ssb.y + ssb.z + ssb.w) + (ssc.x + ssc.y + ssc.z + ssc.w) + (ssd.x + ssd.y + ssd.z + ssd.w);
;     rr[tid] = rsqrtf(ss * (1.f / 1024.f) + 1e-6f);
;   }
.LBB0_1192:
	s_lshl_b32 s10, s36, 7
	s_ashr_i32 s11, s10, 31
	v_mov_b32_e32 v92, v158
	s_lshl_b32 s0, s37, 7
	s_lshl_b64 s[4:5], s[10:11], 11
	s_add_u32 s12, s74, s4
	v_and_b32_e32 v0, 0x7f, v92
	s_addc_u32 s13, s75, s5
	s_ashr_i32 s1, s0, 31
	v_or_b32_e32 v2, s10, v0
	s_add_u32 s14, s31, s0
	v_ashrrev_i32_e32 v3, 31, v2
	s_addc_u32 s15, s30, s1
	v_lshlrev_b64 v[2:3], 6, v[2:3]
	s_lshl_b64 s[14:15], s[14:15], 11
	v_lshl_add_u64 v[2:3], s[66:67], 0, v[2:3]
	v_mov_b32_e32 v16, v158
	s_add_u32 s14, s90, s14
	s_waitcnt vmcnt(63) expcnt(7) lgkmcnt(15)
	s_barrier
	global_load_dwordx4 v[66:69], v[2:3], off offset:48
	global_load_dwordx4 v[70:73], v[2:3], off offset:32
	global_load_dwordx4 v[74:77], v[2:3], off offset:16
	global_load_dwordx4 v[78:81], v[2:3], off
	s_addc_u32 s15, s91, s15
	v_ashrrev_i32_e32 v2, 3, v16
	v_lshrrev_b32_e32 v17, 4, v16
	v_ashrrev_i32_e32 v3, 31, v2
	v_xor_b32_e32 v0, v17, v16
	s_cmp_gt_i32 s37, 41
	v_lshlrev_b64 v[4:5], 11, v[2:3]
	v_lshlrev_b32_e32 v0, 4, v0
	v_lshl_add_u64 v[6:7], s[12:13], 0, v[4:5]
	v_and_b32_e32 v0, 0x70, v0
	v_lshlrev_b32_e32 v93, 4, v16
	s_cselect_b32 s12, 63, 0x7f
	v_lshl_add_u64 v[6:7], v[6:7], 0, v[0:1]
	v_lshl_add_u64 v[8:9], s[14:15], 0, v[0:1]
	v_add_u32_e32 v3, 0x4000, v93
	v_readfirstlane_b32 s13, v93
	v_and_b32_e32 v0, s12, v2
	s_mov_b32 m0, s13
	v_lshlrev_b32_e32 v0, 11, v0
	v_readfirstlane_b32 s13, v3
	v_add_u32_e32 v3, 0x1000, v93
	global_load_lds_dwordx4 v[6:7], off
	v_lshl_add_u64 v[10:11], v[8:9], 0, v[0:1]
	s_mov_b32 m0, s13
	s_mov_b64 s[14:15], 0x10000
	v_readfirstlane_b32 s13, v3
	v_add_u32_e32 v3, 32, v2
	global_load_lds_dwordx4 v[10:11], off
	v_lshl_add_u64 v[10:11], v[6:7], 0, s[14:15]
	s_mov_b32 m0, s13
	v_and_b32_e32 v3, s12, v3
	global_load_lds_dwordx4 v[10:11], off
	v_lshlrev_b32_e32 v10, 11, v3
	v_add_u32_e32 v3, 0x5000, v93
	v_mov_b32_e32 v11, v1
	v_readfirstlane_b32 s13, v3
	v_add_u32_e32 v3, 0x2000, v93
	v_lshl_add_u64 v[12:13], v[8:9], 0, v[10:11]
	s_mov_b32 m0, s13
	v_readfirstlane_b32 s13, v3
	global_load_lds_dwordx4 v[12:13], off
	v_lshl_add_u64 v[12:13], v[6:7], 0, s[60:61]
	s_mov_b32 m0, s13
	v_bitop3_b32 v3, v2, s12, 64 bitop3:0x48
	global_load_lds_dwordx4 v[12:13], off
	v_lshlrev_b32_e32 v12, 11, v3
	v_add_u32_e32 v3, 0x6000, v93
	v_mov_b32_e32 v13, v1
	v_readfirstlane_b32 s13, v3
	v_add_u32_e32 v3, 0x3000, v93
	v_add_u32_e32 v2, 0x60, v2
	v_lshl_add_u64 v[14:15], v[8:9], 0, v[12:13]
	s_mov_b32 m0, s13
	s_mov_b64 s[14:15], 0x30000
	v_readfirstlane_b32 s13, v3
	v_and_b32_e32 v2, s12, v2
	global_load_lds_dwordx4 v[14:15], off
	v_lshl_add_u64 v[6:7], v[6:7], 0, s[14:15]
	s_mov_b32 m0, s13
	v_lshlrev_b32_e32 v2, 11, v2
	v_mov_b32_e32 v3, v1
	global_load_lds_dwordx4 v[6:7], off
	v_lshl_add_u64 v[6:7], v[8:9], 0, v[2:3]
	v_add_u32_e32 v3, 0x7000, v93
	v_readfirstlane_b32 s11, v16
	v_readfirstlane_b32 s12, v3
	s_mov_b32 m0, s12
	s_lshl_b32 s12, s11, 7
	global_load_lds_dwordx4 v[6:7], off
	v_lshlrev_b32_e32 v3, 7, v16
	s_lshl_b32 s11, s11, 6
	v_bfe_u32 v18, v16, 4, 2
	v_bfe_u32 v20, v16, 1, 3
	s_and_b32 s12, s12, 0x2000
	v_and_b32_e32 v3, 0x780, v3
	s_and_b32 s11, s11, 0xffffe000
	v_or_b32_e32 v94, s12, v3
	v_or_b32_e32 v96, s11, v3
	v_bitop3_b32 v3, v18, v20, 4 bitop3:0x36
	v_lshlrev_b32_e32 v95, 4, v3
	v_bitop3_b32 v3, v17, 7, v16 bitop3:0x48
	v_lshlrev_b32_e32 v3, 4, v3
	v_or_b32_e32 v82, v4, v3
	s_lshl_b64 s[0:1], s[0:1], 11
	s_add_u32 s12, s74, s4
	s_addc_u32 s13, s75, s5
	v_readfirstlane_b32 s33, v93
	s_add_u32 s12, s12, 0x80
	s_addc_u32 s13, s13, 0
	v_add_u32_e32 v83, 0x10000, v82
	v_add_u32_e32 v84, 0x20000, v82
	v_add_u32_e32 v85, 0x30000, v82
	s_add_u32 s14, s2, s0
	s_addc_u32 s15, s3, s1
	v_or_b32_e32 v86, v0, v3
	v_or_b32_e32 v87, v10, v3
	v_lshrrev_b32_e32 v19, 1, v16
	v_or_b32_e32 v88, v12, v3
	v_bitop3_b32 v6, v19, v18, 7 bitop3:0x6c
	v_or_b32_e32 v89, v2, v3
	v_mov_b32_e32 v2, 0
	v_lshlrev_b32_e32 v97, 4, v6
	s_mov_b64 s[0:1], 0
	s_mov_b32 s4, 0
	v_mov_b32_e32 v3, 0
	v_mov_b64_e32 v[4:5], v[2:3]
	v_mov_b64_e32 v[6:7], v[2:3]
	v_mov_b64_e32 v[8:9], v[2:3]
	v_mov_b64_e32 v[10:11], v[2:3]
	v_mov_b64_e32 v[12:13], v[2:3]
	v_mov_b64_e32 v[14:15], v[2:3]
	v_mov_b64_e32 v[16:17], v[2:3]
	v_mov_b64_e32 v[18:19], v[2:3]
	v_mov_b64_e32 v[20:21], v[2:3]
	v_mov_b64_e32 v[22:23], v[2:3]
	v_mov_b64_e32 v[24:25], v[2:3]
	v_mov_b64_e32 v[26:27], v[2:3]
	v_mov_b64_e32 v[28:29], v[2:3]
	v_mov_b64_e32 v[30:31], v[2:3]
	v_mov_b64_e32 v[32:33], v[2:3]
	v_mov_b64_e32 v[34:35], v[2:3]
	v_mov_b64_e32 v[36:37], v[2:3]
	v_mov_b64_e32 v[38:39], v[2:3]
	v_mov_b64_e32 v[40:41], v[2:3]
	v_mov_b64_e32 v[42:43], v[2:3]
	v_mov_b64_e32 v[44:45], v[2:3]
	v_mov_b64_e32 v[46:47], v[2:3]
	v_mov_b64_e32 v[48:49], v[2:3]
	v_mov_b64_e32 v[50:51], v[2:3]
	v_mov_b64_e32 v[52:53], v[2:3]
	v_mov_b64_e32 v[54:55], v[2:3]
	v_mov_b64_e32 v[56:57], v[2:3]
	v_mov_b64_e32 v[58:59], v[2:3]
	v_mov_b64_e32 v[60:61], v[2:3]
	v_mov_b64_e32 v[62:63], v[2:3]
	v_mov_b64_e32 v[64:65], v[2:3]
	s_waitcnt vmcnt(8)
	v_cmp_gt_i32_e32 vcc, 0x80, v92
	s_and_saveexec_b64 s[98:99], vcc
	v_mov_b32_e32 v98, v78
	v_mov_b32_e32 v99, v74
	v_mov_b32_e32 v74, v79
	v_pk_add_f32 v[74:75], v[98:99], v[74:75]
	v_mov_b32_e32 v78, v80
	v_mov_b32_e32 v79, v76
	v_pk_add_f32 v[74:75], v[78:79], v[74:75]
	v_mov_b32_e32 v76, v81
	v_pk_add_f32 v[74:75], v[76:77], v[74:75]
	v_mov_b32_e32 v76, v70
	v_mov_b32_e32 v77, v66
	v_mov_b32_e32 v66, v71
	v_pk_add_f32 v[66:67], v[76:77], v[66:67]
	v_mov_b32_e32 v70, v72
	v_mov_b32_e32 v71, v68
	v_pk_add_f32 v[66:67], v[70:71], v[66:67]
	v_mov_b32_e32 v68, v73
	v_pk_add_f32 v[66:67], v[68:69], v[66:67]
	v_add_f32_e32 v0, v74, v75
	v_add_f32_e32 v0, v0, v66
	v_add_f32_e32 v0, v0, v67
	v_fmamk_f32 v0, v0, 0x3a800000, v160
	s_mov_b32 s5, 0x800000
	v_mul_f32_e32 v66, 0x4b800000, v0
	v_cmp_gt_f32_e32 vcc, s5, v0
	s_nop 1
	v_cndmask_b32_e32 v0, v0, v66, vcc
	v_rsq_f32_e32 v0, v0
	s_nop 0
	v_mul_f32_e32 v66, 0x45800000, v0
	v_cndmask_b32_e32 v0, v0, v66, vcc
	v_lshl_add_u32 v66, v92, 2, v173
	ds_write_b32 v66, v0
	s_or_b64 exec, exec, s[98:99]
	v_add_u32_e32 v184, v97, v96
	v_add_u32_e32 v185, v97, v94
	s_waitcnt vmcnt(0) lgkmcnt(0)
	s_barrier
	.p2alignl 6, 3212836864
; #define MFMA16(a, b, c) __builtin_amdgcn_mfma_f32_16x16x32_bf16((a), (b), (c), 0, 0, 0)
; DI void gemm_tile(const bf16_t* __restrict__ A, int lda, const bf16_t* __restrict__ Bt, int ldb, int bvalid, int K, f32x4 (&acc)[4][4], char* lds, bool preloaded = false) {
;     ...
;   auto compute = [&](int st) {
;     const char* base = lds + st * 32768;
;     bf16x8 af[2][4], bfr[2][4];
; #pragma unroll
;     for (int s = 0; s < 2; ++s) {
;       const int ch = ((4 * s + fq) ^ fx) << 4;
; #pragma unroll
;       for (int mi = 0; mi < 4; ++mi) af[s][mi] = *(const bf16x8*)(base + (wm * 64 + mi * 16 + fr) * 128 + ch);
; #pragma unroll
;       for (int ni = 0; ni < 4; ++ni) bfr[s][ni] = *(const bf16x8*)(base + 16384 + (wn * 64 + ni * 16 + fr) * 128 + ch);
;     }
;     __builtin_amdgcn_s_setprio(1);
; #pragma unroll
;     for (int s = 0; s < 2; ++s)
; #pragma unroll
;       for (int mi = 0; mi < 4; ++mi)
; #pragma unroll
;         for (int ni = 0; ni < 4; ++ni) acc[mi][ni] = MFMA16(af[s][mi], bfr[s][ni], acc[mi][ni]);
;     __builtin_amdgcn_s_setprio(0);
;   };
;   const int nk = K >> 6;
;   if (!preloaded) { GLDS(0, 0) }
;   __syncthreads();
;   for (int kt = 0; kt < nk; ++kt) {
;     if (kt + 1 < nk) { GLDS((kt + 1) & 1, (kt + 1) << 6) }
;     compute(kt & 1);
;     __syncthreads();
.LBB0_1193:
	s_add_i32 s5, s4, 0x8000
	s_and_b32 s11, s5, 0x8000
	s_and_b32 s4, s4, 0x8000
	ds_read_b128 v[98:101], v184
	ds_read_b128 v[114:117], v185 offset:16384
	ds_read_b128 v[118:121], v185 offset:18432
	ds_read_b128 v[122:125], v185 offset:20480
	ds_read_b128 v[126:129], v185 offset:22528
	ds_read_b128 v[102:105], v184 offset:2048
	ds_read_b128 v[106:109], v184 offset:4096
	ds_read_b128 v[110:113], v184 offset:6144
	s_add_i32 m0, s33, s11
	v_or_b32_e32 v0, s4, v95
	global_load_lds_dwordx4 v82, s[12:13]
	s_addk_i32 m0, 0x1000
	v_add_u32_e32 v142, v0, v96
	global_load_lds_dwordx4 v83, s[12:13]
	s_addk_i32 m0, 0x1000
	v_add_u32_e32 v0, v0, v94
	global_load_lds_dwordx4 v84, s[12:13]
	s_addk_i32 m0, 0x1000
	ds_read_b128 v[130:133], v142
	global_load_lds_dwordx4 v85, s[12:13]
	s_addk_i32 m0, 0x1000
	ds_read_b128 v[146:149], v0 offset:16384
	global_load_lds_dwordx4 v86, s[14:15]
	s_addk_i32 m0, 0x1000
	ds_read_b128 v[150:153], v0 offset:18432
	global_load_lds_dwordx4 v87, s[14:15]
	s_addk_i32 m0, 0x1000
	ds_read_b128 v[154:157], v0 offset:20480
	global_load_lds_dwordx4 v88, s[14:15]
	s_addk_i32 m0, 0x1000
	ds_read_b128 v[180:183], v0 offset:22528
	global_load_lds_dwordx4 v89, s[14:15]
	ds_read_b128 v[134:137], v142 offset:2048
	ds_read_b128 v[138:141], v142 offset:4096
	ds_read_b128 v[142:145], v142 offset:6144
	s_add_u32 s12, s12, 0x80
	s_addc_u32 s13, s13, 0
	s_add_u32 s14, s14, 0x80
	s_addc_u32 s15, s15, 0
	s_setprio 1
	s_waitcnt lgkmcnt(11)
	v_mfma_f32_16x16x32_bf16 v[62:65], v[98:101], v[114:117], v[62:65]
	v_mfma_f32_16x16x32_bf16 v[58:61], v[98:101], v[118:121], v[58:61]
	v_mfma_f32_16x16x32_bf16 v[54:57], v[98:101], v[122:125], v[54:57]
	v_mfma_f32_16x16x32_bf16 v[50:53], v[98:101], v[126:129], v[50:53]
	s_waitcnt lgkmcnt(8)
	v_mfma_f32_16x16x32_bf16 v[46:49], v[102:105], v[114:117], v[46:49]
	v_mfma_f32_16x16x32_bf16 v[42:45], v[102:105], v[118:121], v[42:45]
	v_mfma_f32_16x16x32_bf16 v[38:41], v[102:105], v[122:125], v[38:41]
	v_mfma_f32_16x16x32_bf16 v[34:37], v[102:105], v[126:129], v[34:37]
	v_mfma_f32_16x16x32_bf16 v[30:33], v[106:109], v[114:117], v[30:33]
	v_mfma_f32_16x16x32_bf16 v[26:29], v[106:109], v[118:121], v[26:29]
	v_mfma_f32_16x16x32_bf16 v[22:25], v[106:109], v[122:125], v[22:25]
	v_mfma_f32_16x16x32_bf16 v[18:21], v[106:109], v[126:129], v[18:21]
	v_mfma_f32_16x16x32_bf16 v[14:17], v[110:113], v[114:117], v[14:17]
	v_mfma_f32_16x16x32_bf16 v[10:13], v[110:113], v[118:121], v[10:13]
	v_mfma_f32_16x16x32_bf16 v[6:9], v[110:113], v[122:125], v[6:9]
	v_mfma_f32_16x16x32_bf16 v[2:5], v[110:113], v[126:129], v[2:5]
	s_waitcnt lgkmcnt(3)
	v_mfma_f32_16x16x32_bf16 v[62:65], v[130:133], v[146:149], v[62:65]
	v_mfma_f32_16x16x32_bf16 v[58:61], v[130:133], v[150:153], v[58:61]
	v_mfma_f32_16x16x32_bf16 v[54:57], v[130:133], v[154:157], v[54:57]
	v_mfma_f32_16x16x32_bf16 v[50:53], v[130:133], v[180:183], v[50:53]
	s_waitcnt lgkmcnt(0)
	v_mfma_f32_16x16x32_bf16 v[46:49], v[134:137], v[146:149], v[46:49]
	v_mfma_f32_16x16x32_bf16 v[42:45], v[134:137], v[150:153], v[42:45]
	v_mfma_f32_16x16x32_bf16 v[38:41], v[134:137], v[154:157], v[38:41]
	v_mfma_f32_16x16x32_bf16 v[34:37], v[134:137], v[180:183], v[34:37]
	v_mfma_f32_16x16x32_bf16 v[30:33], v[138:141], v[146:149], v[30:33]
	v_mfma_f32_16x16x32_bf16 v[26:29], v[138:141], v[150:153], v[26:29]
	v_mfma_f32_16x16x32_bf16 v[22:25], v[138:141], v[154:157], v[22:25]
	v_mfma_f32_16x16x32_bf16 v[18:21], v[138:141], v[180:183], v[18:21]
	v_mfma_f32_16x16x32_bf16 v[14:17], v[142:145], v[146:149], v[14:17]
	v_mfma_f32_16x16x32_bf16 v[10:13], v[142:145], v[150:153], v[10:13]
	v_mfma_f32_16x16x32_bf16 v[6:9], v[142:145], v[154:157], v[6:9]
	v_mfma_f32_16x16x32_bf16 v[2:5], v[142:145], v[180:183], v[2:5]
	s_setprio 0
	v_or_b32_e32 v0, s11, v97
	v_add_u32_e32 v184, v0, v96
	v_add_u32_e32 v185, v0, v94
	s_add_u32 s0, s0, 0x80
	s_cmpk_eq_i32 s0, 0x780
	s_mov_b32 s4, s5
	s_waitcnt vmcnt(0)
	s_barrier
; #define MFMA16(a, b, c) __builtin_amdgcn_mfma_f32_16x16x32_bf16((a), (b), (c), 0, 0, 0)
; DI void gemm_tile(const bf16_t* __restrict__ A, int lda, const bf16_t* __restrict__ Bt, int ldb, int bvalid, int K, f32x4 (&acc)[4][4], char* lds, bool preloaded = false) {
;     ...
;   auto compute = [&](int st) {
;     const char* base = lds + st * 32768;
;     bf16x8 af[2][4], bfr[2][4];
; #pragma unroll
;     for (int s = 0; s < 2; ++s) {
;       const int ch = ((4 * s + fq) ^ fx) << 4;
; #pragma unroll
;       for (int mi = 0; mi < 4; ++mi) af[s][mi] = *(const bf16x8*)(base + (wm * 64 + mi * 16 + fr) * 128 + ch);
; #pragma unroll
;       for (int ni = 0; ni < 4; ++ni) bfr[s][ni] = *(const bf16x8*)(base + 16384 + (wn * 64 + ni * 16 + fr) * 128 + ch);
;     }
;     __builtin_amdgcn_s_setprio(1);
; #pragma unroll
;     for (int s = 0; s < 2; ++s)
; #pragma unroll
;       for (int mi = 0; mi < 4; ++mi)
; #pragma unroll
;         for (int ni = 0; ni < 4; ++ni) acc[mi][ni] = MFMA16(af[s][mi], bfr[s][ni], acc[mi][ni]);
;     __builtin_amdgcn_s_setprio(0);
; DI void phaseA_tile(const P& p, int layer, int mt, int nt, char* lds) {
;     ...
;   float* stg = (float*)lds;
;   stage_acc(acc, stg, wm, wn, fr, fq);
;   __syncthreads();
;   if (seg >= NSEG) return;
	s_cbranch_scc0 .LBB0_1193
	v_add_u32_e32 v0, v97, v96
	ds_read_b128 v[82:85], v0 offset:32768
	ds_read_b128 v[86:89], v0 offset:34816
	ds_read_b128 v[98:101], v0 offset:36864
	ds_read_b128 v[102:105], v0 offset:38912
	v_add_u32_e32 v0, v97, v94
	ds_read_b128 v[106:109], v0 offset:49152
	ds_read_b128 v[110:113], v0 offset:51200
	ds_read_b128 v[114:117], v0 offset:53248
	ds_read_b128 v[118:121], v0 offset:55296
	v_add_u32_e32 v0, v95, v96
	ds_read_b128 v[122:125], v0 offset:32768
	ds_read_b128 v[126:129], v0 offset:34816
	ds_read_b128 v[130:133], v0 offset:36864
	ds_read_b128 v[134:137], v0 offset:38912
	v_add_u32_e32 v0, v95, v94
	ds_read_b128 v[94:97], v0 offset:49152
	ds_read_b128 v[138:141], v0 offset:51200
	ds_read_b128 v[142:145], v0 offset:53248
	ds_read_b128 v[146:149], v0 offset:55296
	s_movk_i32 s33, 0x210
	v_readfirstlane_b32 s4, v92
	s_setprio 1
	s_waitcnt lgkmcnt(11)
	v_mfma_f32_16x16x32_bf16 v[62:65], v[82:85], v[106:109], v[62:65]
	s_waitcnt lgkmcnt(10)
	v_mfma_f32_16x16x32_bf16 v[58:61], v[82:85], v[110:113], v[58:61]
	s_waitcnt lgkmcnt(9)
	v_mfma_f32_16x16x32_bf16 v[54:57], v[82:85], v[114:117], v[54:57]
	s_waitcnt lgkmcnt(8)
	v_mfma_f32_16x16x32_bf16 v[50:53], v[82:85], v[118:121], v[50:53]
	v_mfma_f32_16x16x32_bf16 v[46:49], v[86:89], v[106:109], v[46:49]
	v_mfma_f32_16x16x32_bf16 v[42:45], v[86:89], v[110:113], v[42:45]
	v_mfma_f32_16x16x32_bf16 v[38:41], v[86:89], v[114:117], v[38:41]
	v_mfma_f32_16x16x32_bf16 v[34:37], v[86:89], v[118:121], v[34:37]
	v_mfma_f32_16x16x32_bf16 v[30:33], v[98:101], v[106:109], v[30:33]
	v_mfma_f32_16x16x32_bf16 v[26:29], v[98:101], v[110:113], v[26:29]
	v_mfma_f32_16x16x32_bf16 v[22:25], v[98:101], v[114:117], v[22:25]
	v_mfma_f32_16x16x32_bf16 v[18:21], v[98:101], v[118:121], v[18:21]
	v_mfma_f32_16x16x32_bf16 v[14:17], v[102:105], v[106:109], v[14:17]
	v_mfma_f32_16x16x32_bf16 v[10:13], v[102:105], v[110:113], v[10:13]
	v_mfma_f32_16x16x32_bf16 v[6:9], v[102:105], v[114:117], v[6:9]
	v_mfma_f32_16x16x32_bf16 v[2:5], v[102:105], v[118:121], v[2:5]
	s_waitcnt lgkmcnt(3)
	v_mfma_f32_16x16x32_bf16 v[62:65], v[122:125], v[94:97], v[62:65]
	s_waitcnt lgkmcnt(2)
	v_mfma_f32_16x16x32_bf16 v[58:61], v[122:125], v[138:141], v[58:61]
	s_waitcnt lgkmcnt(1)
	v_mfma_f32_16x16x32_bf16 v[54:57], v[122:125], v[142:145], v[54:57]
	s_waitcnt lgkmcnt(0)
	v_mfma_f32_16x16x32_bf16 v[50:53], v[122:125], v[146:149], v[50:53]
	v_mfma_f32_16x16x32_bf16 v[46:49], v[126:129], v[94:97], v[46:49]
	v_mfma_f32_16x16x32_bf16 v[42:45], v[126:129], v[138:141], v[42:45]
	v_mfma_f32_16x16x32_bf16 v[38:41], v[126:129], v[142:145], v[38:41]
	v_mfma_f32_16x16x32_bf16 v[34:37], v[126:129], v[146:149], v[34:37]
	v_mfma_f32_16x16x32_bf16 v[30:33], v[130:133], v[94:97], v[30:33]
	v_mfma_f32_16x16x32_bf16 v[26:29], v[130:133], v[138:141], v[26:29]
	v_mfma_f32_16x16x32_bf16 v[22:25], v[130:133], v[142:145], v[22:25]
	v_mfma_f32_16x16x32_bf16 v[18:21], v[130:133], v[146:149], v[18:21]
	v_mfma_f32_16x16x32_bf16 v[14:17], v[134:137], v[94:97], v[14:17]
	v_mfma_f32_16x16x32_bf16 v[10:13], v[134:137], v[138:141], v[10:13]
	v_mfma_f32_16x16x32_bf16 v[6:9], v[134:137], v[142:145], v[6:9]
	v_mfma_f32_16x16x32_bf16 v[2:5], v[134:137], v[146:149], v[2:5]
	s_setprio 0
	s_cmp_gt_i32 s37, 26
	s_cbranch_scc1 .Lnob1_a1
	s_barrier
